# SSD scan: two-chunk sequences handled by a fast path with all 48 loads of a thread in flight (final-state fma + non-temporal stores), generic loop only for the long sequences
# baseline (speedup 1.0000x reference)
.LBB0_2039:
	s_or_b64 exec, exec, s[0:1]
	s_mov_b64 s[6:7], s[60:61]
	s_mov_b64 s[2:3], s[60:61]
	s_mov_b64 s[4:5], s[60:61]
	s_waitcnt lgkmcnt(0)
	v_mov_b32_e32 v0, v219
	s_barrier
	s_mov_b32 s0, 0x240000
	v_readfirstlane_b32 s10, v0
	v_mov_b32_e32 v0, v218
	s_nop 0
	v_lshl_add_u32 v67, s10, 8, v0
	v_cmp_gt_i32_e32 vcc, s0, v67
	s_and_saveexec_b64 s[0:1], vcc
	s_cbranch_execz .LBB0_2046
	s_load_dwordx2 s[6:7], s[6:7], 0xe8
	s_nop 0
	s_load_dwordx2 s[2:3], s[2:3], 0x10
	s_nop 0
	s_load_dwordx2 s[12:13], s[4:5], 0xe0
	v_lshlrev_b32_e32 v0, 3, v0
	v_lshl_add_u32 v71, s10, 11, v0
	s_waitcnt lgkmcnt(0)
	s_add_u32 s4, s6, 0x1108000
	s_addc_u32 s5, s7, 0
	s_add_u32 s6, s12, 0x4000000
	s_addc_u32 s7, s13, 0
	s_and_b64 s[10:11], s[8:9], exec
	s_cselect_b32 s14, 2, 0
	s_mov_b64 s[10:11], 0
	v_readlane_b32 s15, v252, 4
	s_cmp_eq_u32 s15, 0x20000
	s_cbranch_scc0 .LBB0_2042
	v_and_b32_e32 v0, 0x78, v71
	v_bfe_u32 v1, v67, 4, 6
	v_bfe_u32 v2, v67, 10, 5
	v_bfe_u32 v3, v67, 15, 1
	v_lshrrev_b32_e32 v4, 16, v67
	v_lshl_or_b32 v5, v3, 5, v2
	v_lshlrev_b32_e32 v5, 14, v5
	v_lshl_add_u32 v5, v1, 8, v5
	v_lshl_add_u32 v5, v0, 1, v5
	v_lshl_or_b32 v6, v4, 1, v3
	v_xor_b32_e32 v7, 1, v6
	v_lshl_add_u32 v8, v6, 20, v5
	v_lshl_add_u32 v9, v7, 20, v5
	v_lshl_or_b32 v10, v3, 5, v2
	v_lshl_or_b32 v10, v7, 6, v10
	v_lshlrev_b32_e32 v10, 2, v10
	v_lshl_or_b32 v11, v4, 2, v3
	v_or_b32_e32 v11, s14, v11
	v_lshlrev_b32_e32 v11, 20, v11
	v_lshl_add_u32 v11, v2, 15, v11
	v_lshl_add_u32 v11, v1, 9, v11
	v_lshl_add_u32 v11, v0, 2, v11
	v_readlane_b32 s12, v252, 49
	v_readlane_b32 s13, v252, 50
	s_mov_b64 s[16:17], s[4:5]
	s_mov_b64 s[100:101], s[6:7]
	s_nop 2
	global_load_dwordx4 v[16:19], v8, s[12:13]
	global_load_dwordx4 v[20:23], v9, s[12:13]
	global_load_dword v184, v10, s[16:17]
	s_add_u32 s12, s12, 0x400000
	s_addc_u32 s13, s13, 0
	s_add_u32 s16, s16, 0x400
	s_addc_u32 s17, s17, 0
	global_load_dwordx4 v[24:27], v8, s[12:13]
	global_load_dwordx4 v[28:31], v9, s[12:13]
	global_load_dword v185, v10, s[16:17]
	s_add_u32 s12, s12, 0x400000
	s_addc_u32 s13, s13, 0
	s_add_u32 s16, s16, 0x400
	s_addc_u32 s17, s17, 0
	global_load_dwordx4 v[32:35], v8, s[12:13]
	global_load_dwordx4 v[36:39], v9, s[12:13]
	global_load_dword v186, v10, s[16:17]
	s_add_u32 s12, s12, 0x400000
	s_addc_u32 s13, s13, 0
	s_add_u32 s16, s16, 0x400
	s_addc_u32 s17, s17, 0
	global_load_dwordx4 v[40:43], v8, s[12:13]
	global_load_dwordx4 v[44:47], v9, s[12:13]
	global_load_dword v187, v10, s[16:17]
	s_add_u32 s12, s12, 0x400000
	s_addc_u32 s13, s13, 0
	s_add_u32 s16, s16, 0x400
	s_addc_u32 s17, s17, 0
	global_load_dwordx4 v[48:51], v8, s[12:13]
	global_load_dwordx4 v[52:55], v9, s[12:13]
	global_load_dword v188, v10, s[16:17]
	s_add_u32 s12, s12, 0x400000
	s_addc_u32 s13, s13, 0
	s_add_u32 s16, s16, 0x400
	s_addc_u32 s17, s17, 0
	global_load_dwordx4 v[56:59], v8, s[12:13]
	global_load_dwordx4 v[60:63], v9, s[12:13]
	global_load_dword v189, v10, s[16:17]
	s_add_u32 s12, s12, 0x400000
	s_addc_u32 s13, s13, 0
	s_add_u32 s16, s16, 0x400
	s_addc_u32 s17, s17, 0
	global_load_dwordx4 v[72:75], v8, s[12:13]
	global_load_dwordx4 v[76:79], v9, s[12:13]
	global_load_dword v190, v10, s[16:17]
	s_add_u32 s12, s12, 0x400000
	s_addc_u32 s13, s13, 0
	s_add_u32 s16, s16, 0x400
	s_addc_u32 s17, s17, 0
	global_load_dwordx4 v[80:83], v8, s[12:13]
	global_load_dwordx4 v[84:87], v9, s[12:13]
	global_load_dword v191, v10, s[16:17]
	s_add_u32 s12, s12, 0x400000
	s_addc_u32 s13, s13, 0
	s_add_u32 s16, s16, 0x400
	s_addc_u32 s17, s17, 0
	global_load_dwordx4 v[88:91], v8, s[12:13]
	global_load_dwordx4 v[92:95], v9, s[12:13]
	global_load_dword v192, v10, s[16:17]
	s_add_u32 s12, s12, 0x400000
	s_addc_u32 s13, s13, 0
	s_add_u32 s16, s16, 0x400
	s_addc_u32 s17, s17, 0
	global_load_dwordx4 v[96:99], v8, s[12:13]
	global_load_dwordx4 v[100:103], v9, s[12:13]
	global_load_dword v193, v10, s[16:17]
	s_add_u32 s12, s12, 0x400000
	s_addc_u32 s13, s13, 0
	s_add_u32 s16, s16, 0x400
	s_addc_u32 s17, s17, 0
	global_load_dwordx4 v[104:107], v8, s[12:13]
	global_load_dwordx4 v[108:111], v9, s[12:13]
	global_load_dword v194, v10, s[16:17]
	s_add_u32 s12, s12, 0x400000
	s_addc_u32 s13, s13, 0
	s_add_u32 s16, s16, 0x400
	s_addc_u32 s17, s17, 0
	global_load_dwordx4 v[112:115], v8, s[12:13]
	global_load_dwordx4 v[116:119], v9, s[12:13]
	global_load_dword v195, v10, s[16:17]
	s_add_u32 s12, s12, 0x400000
	s_addc_u32 s13, s13, 0
	s_add_u32 s16, s16, 0x400
	s_addc_u32 s17, s17, 0
	global_load_dwordx4 v[120:123], v8, s[12:13]
	global_load_dwordx4 v[124:127], v9, s[12:13]
	global_load_dword v196, v10, s[16:17]
	s_add_u32 s12, s12, 0x400000
	s_addc_u32 s13, s13, 0
	s_add_u32 s16, s16, 0x400
	s_addc_u32 s17, s17, 0
	global_load_dwordx4 v[132:135], v8, s[12:13]
	global_load_dwordx4 v[136:139], v9, s[12:13]
	global_load_dword v197, v10, s[16:17]
	s_add_u32 s12, s12, 0x400000
	s_addc_u32 s13, s13, 0
	s_add_u32 s16, s16, 0x400
	s_addc_u32 s17, s17, 0
	global_load_dwordx4 v[140:143], v8, s[12:13]
	global_load_dwordx4 v[144:147], v9, s[12:13]
	global_load_dword v198, v10, s[16:17]
	s_add_u32 s12, s12, 0x400000
	s_addc_u32 s13, s13, 0
	s_add_u32 s16, s16, 0x400
	s_addc_u32 s17, s17, 0
	global_load_dwordx4 v[148:151], v8, s[12:13]
	global_load_dwordx4 v[152:155], v9, s[12:13]
	global_load_dword v199, v10, s[16:17]
	s_waitcnt vmcnt(45)
	v_lshlrev_b32_e32 v200, 16, v20
	v_and_b32_e32 v201, 0xffff0000, v20
	v_lshlrev_b32_e32 v202, 16, v21
	v_and_b32_e32 v203, 0xffff0000, v21
	v_lshlrev_b32_e32 v204, 16, v22
	v_and_b32_e32 v205, 0xffff0000, v22
	v_lshlrev_b32_e32 v206, 16, v23
	v_and_b32_e32 v207, 0xffff0000, v23
	v_lshlrev_b32_e32 v20, 16, v16
	v_and_b32_e32 v16, 0xffff0000, v16
	v_fma_f32 v200, v184, v20, v200
	v_fma_f32 v201, v184, v16, v201
	v_lshlrev_b32_e32 v21, 16, v17
	v_and_b32_e32 v17, 0xffff0000, v17
	v_fma_f32 v202, v184, v21, v202
	v_fma_f32 v203, v184, v17, v203
	v_lshlrev_b32_e32 v22, 16, v18
	v_and_b32_e32 v18, 0xffff0000, v18
	v_fma_f32 v204, v184, v22, v204
	v_fma_f32 v205, v184, v18, v205
	v_lshlrev_b32_e32 v23, 16, v19
	v_and_b32_e32 v19, 0xffff0000, v19
	v_fma_f32 v206, v184, v23, v206
	v_fma_f32 v207, v184, v19, v207
	global_store_dwordx4 v11, v[200:203], s[100:101] nt
	global_store_dwordx4 v11, v[204:207], s[100:101] offset:16 nt
	s_add_u32 s100, s100, 0x800000
	s_addc_u32 s101, s101, 0
	s_waitcnt vmcnt(44)
	v_lshlrev_b32_e32 v208, 16, v28
	v_and_b32_e32 v209, 0xffff0000, v28
	v_lshlrev_b32_e32 v210, 16, v29
	v_and_b32_e32 v211, 0xffff0000, v29
	v_lshlrev_b32_e32 v212, 16, v30
	v_and_b32_e32 v213, 0xffff0000, v30
	v_lshlrev_b32_e32 v214, 16, v31
	v_and_b32_e32 v215, 0xffff0000, v31
	v_lshlrev_b32_e32 v28, 16, v24
	v_and_b32_e32 v24, 0xffff0000, v24
	v_fma_f32 v208, v185, v28, v208
	v_fma_f32 v209, v185, v24, v209
	v_lshlrev_b32_e32 v29, 16, v25
	v_and_b32_e32 v25, 0xffff0000, v25
	v_fma_f32 v210, v185, v29, v210
	v_fma_f32 v211, v185, v25, v211
	v_lshlrev_b32_e32 v30, 16, v26
	v_and_b32_e32 v26, 0xffff0000, v26
	v_fma_f32 v212, v185, v30, v212
	v_fma_f32 v213, v185, v26, v213
	v_lshlrev_b32_e32 v31, 16, v27
	v_and_b32_e32 v27, 0xffff0000, v27
	v_fma_f32 v214, v185, v31, v214
	v_fma_f32 v215, v185, v27, v215
	global_store_dwordx4 v11, v[208:211], s[100:101] nt
	global_store_dwordx4 v11, v[212:215], s[100:101] offset:16 nt
	s_add_u32 s100, s100, 0x800000
	s_addc_u32 s101, s101, 0
	s_waitcnt vmcnt(43)
	v_lshlrev_b32_e32 v200, 16, v36
	v_and_b32_e32 v201, 0xffff0000, v36
	v_lshlrev_b32_e32 v202, 16, v37
	v_and_b32_e32 v203, 0xffff0000, v37
	v_lshlrev_b32_e32 v204, 16, v38
	v_and_b32_e32 v205, 0xffff0000, v38
	v_lshlrev_b32_e32 v206, 16, v39
	v_and_b32_e32 v207, 0xffff0000, v39
	v_lshlrev_b32_e32 v36, 16, v32
	v_and_b32_e32 v32, 0xffff0000, v32
	v_fma_f32 v200, v186, v36, v200
	v_fma_f32 v201, v186, v32, v201
	v_lshlrev_b32_e32 v37, 16, v33
	v_and_b32_e32 v33, 0xffff0000, v33
	v_fma_f32 v202, v186, v37, v202
	v_fma_f32 v203, v186, v33, v203
	v_lshlrev_b32_e32 v38, 16, v34
	v_and_b32_e32 v34, 0xffff0000, v34
	v_fma_f32 v204, v186, v38, v204
	v_fma_f32 v205, v186, v34, v205
	v_lshlrev_b32_e32 v39, 16, v35
	v_and_b32_e32 v35, 0xffff0000, v35
	v_fma_f32 v206, v186, v39, v206
	v_fma_f32 v207, v186, v35, v207
	global_store_dwordx4 v11, v[200:203], s[100:101] nt
	global_store_dwordx4 v11, v[204:207], s[100:101] offset:16 nt
	s_add_u32 s100, s100, 0x800000
	s_addc_u32 s101, s101, 0
	s_waitcnt vmcnt(42)
	v_lshlrev_b32_e32 v208, 16, v44
	v_and_b32_e32 v209, 0xffff0000, v44
	v_lshlrev_b32_e32 v210, 16, v45
	v_and_b32_e32 v211, 0xffff0000, v45
	v_lshlrev_b32_e32 v212, 16, v46
	v_and_b32_e32 v213, 0xffff0000, v46
	v_lshlrev_b32_e32 v214, 16, v47
	v_and_b32_e32 v215, 0xffff0000, v47
	v_lshlrev_b32_e32 v44, 16, v40
	v_and_b32_e32 v40, 0xffff0000, v40
	v_fma_f32 v208, v187, v44, v208
	v_fma_f32 v209, v187, v40, v209
	v_lshlrev_b32_e32 v45, 16, v41
	v_and_b32_e32 v41, 0xffff0000, v41
	v_fma_f32 v210, v187, v45, v210
	v_fma_f32 v211, v187, v41, v211
	v_lshlrev_b32_e32 v46, 16, v42
	v_and_b32_e32 v42, 0xffff0000, v42
	v_fma_f32 v212, v187, v46, v212
	v_fma_f32 v213, v187, v42, v213
	v_lshlrev_b32_e32 v47, 16, v43
	v_and_b32_e32 v43, 0xffff0000, v43
	v_fma_f32 v214, v187, v47, v214
	v_fma_f32 v215, v187, v43, v215
	global_store_dwordx4 v11, v[208:211], s[100:101] nt
	global_store_dwordx4 v11, v[212:215], s[100:101] offset:16 nt
	s_add_u32 s100, s100, 0x800000
	s_addc_u32 s101, s101, 0
	s_waitcnt vmcnt(41)
	v_lshlrev_b32_e32 v200, 16, v52
	v_and_b32_e32 v201, 0xffff0000, v52
	v_lshlrev_b32_e32 v202, 16, v53
	v_and_b32_e32 v203, 0xffff0000, v53
	v_lshlrev_b32_e32 v204, 16, v54
	v_and_b32_e32 v205, 0xffff0000, v54
	v_lshlrev_b32_e32 v206, 16, v55
	v_and_b32_e32 v207, 0xffff0000, v55
	v_lshlrev_b32_e32 v52, 16, v48
	v_and_b32_e32 v48, 0xffff0000, v48
	v_fma_f32 v200, v188, v52, v200
	v_fma_f32 v201, v188, v48, v201
	v_lshlrev_b32_e32 v53, 16, v49
	v_and_b32_e32 v49, 0xffff0000, v49
	v_fma_f32 v202, v188, v53, v202
	v_fma_f32 v203, v188, v49, v203
	v_lshlrev_b32_e32 v54, 16, v50
	v_and_b32_e32 v50, 0xffff0000, v50
	v_fma_f32 v204, v188, v54, v204
	v_fma_f32 v205, v188, v50, v205
	v_lshlrev_b32_e32 v55, 16, v51
	v_and_b32_e32 v51, 0xffff0000, v51
	v_fma_f32 v206, v188, v55, v206
	v_fma_f32 v207, v188, v51, v207
	global_store_dwordx4 v11, v[200:203], s[100:101] nt
	global_store_dwordx4 v11, v[204:207], s[100:101] offset:16 nt
	s_add_u32 s100, s100, 0x800000
	s_addc_u32 s101, s101, 0
	s_waitcnt vmcnt(40)
	v_lshlrev_b32_e32 v208, 16, v60
	v_and_b32_e32 v209, 0xffff0000, v60
	v_lshlrev_b32_e32 v210, 16, v61
	v_and_b32_e32 v211, 0xffff0000, v61
	v_lshlrev_b32_e32 v212, 16, v62
	v_and_b32_e32 v213, 0xffff0000, v62
	v_lshlrev_b32_e32 v214, 16, v63
	v_and_b32_e32 v215, 0xffff0000, v63
	v_lshlrev_b32_e32 v60, 16, v56
	v_and_b32_e32 v56, 0xffff0000, v56
	v_fma_f32 v208, v189, v60, v208
	v_fma_f32 v209, v189, v56, v209
	v_lshlrev_b32_e32 v61, 16, v57
	v_and_b32_e32 v57, 0xffff0000, v57
	v_fma_f32 v210, v189, v61, v210
	v_fma_f32 v211, v189, v57, v211
	v_lshlrev_b32_e32 v62, 16, v58
	v_and_b32_e32 v58, 0xffff0000, v58
	v_fma_f32 v212, v189, v62, v212
	v_fma_f32 v213, v189, v58, v213
	v_lshlrev_b32_e32 v63, 16, v59
	v_and_b32_e32 v59, 0xffff0000, v59
	v_fma_f32 v214, v189, v63, v214
	v_fma_f32 v215, v189, v59, v215
	global_store_dwordx4 v11, v[208:211], s[100:101] nt
	global_store_dwordx4 v11, v[212:215], s[100:101] offset:16 nt
	s_add_u32 s100, s100, 0x800000
	s_addc_u32 s101, s101, 0
	s_waitcnt vmcnt(39)
	v_lshlrev_b32_e32 v200, 16, v76
	v_and_b32_e32 v201, 0xffff0000, v76
	v_lshlrev_b32_e32 v202, 16, v77
	v_and_b32_e32 v203, 0xffff0000, v77
	v_lshlrev_b32_e32 v204, 16, v78
	v_and_b32_e32 v205, 0xffff0000, v78
	v_lshlrev_b32_e32 v206, 16, v79
	v_and_b32_e32 v207, 0xffff0000, v79
	v_lshlrev_b32_e32 v76, 16, v72
	v_and_b32_e32 v72, 0xffff0000, v72
	v_fma_f32 v200, v190, v76, v200
	v_fma_f32 v201, v190, v72, v201
	v_lshlrev_b32_e32 v77, 16, v73
	v_and_b32_e32 v73, 0xffff0000, v73
	v_fma_f32 v202, v190, v77, v202
	v_fma_f32 v203, v190, v73, v203
	v_lshlrev_b32_e32 v78, 16, v74
	v_and_b32_e32 v74, 0xffff0000, v74
	v_fma_f32 v204, v190, v78, v204
	v_fma_f32 v205, v190, v74, v205
	v_lshlrev_b32_e32 v79, 16, v75
	v_and_b32_e32 v75, 0xffff0000, v75
	v_fma_f32 v206, v190, v79, v206
	v_fma_f32 v207, v190, v75, v207
	global_store_dwordx4 v11, v[200:203], s[100:101] nt
	global_store_dwordx4 v11, v[204:207], s[100:101] offset:16 nt
	s_add_u32 s100, s100, 0x800000
	s_addc_u32 s101, s101, 0
	s_waitcnt vmcnt(38)
	v_lshlrev_b32_e32 v208, 16, v84
	v_and_b32_e32 v209, 0xffff0000, v84
	v_lshlrev_b32_e32 v210, 16, v85
	v_and_b32_e32 v211, 0xffff0000, v85
	v_lshlrev_b32_e32 v212, 16, v86
	v_and_b32_e32 v213, 0xffff0000, v86
	v_lshlrev_b32_e32 v214, 16, v87
	v_and_b32_e32 v215, 0xffff0000, v87
	v_lshlrev_b32_e32 v84, 16, v80
	v_and_b32_e32 v80, 0xffff0000, v80
	v_fma_f32 v208, v191, v84, v208
	v_fma_f32 v209, v191, v80, v209
	v_lshlrev_b32_e32 v85, 16, v81
	v_and_b32_e32 v81, 0xffff0000, v81
	v_fma_f32 v210, v191, v85, v210
	v_fma_f32 v211, v191, v81, v211
	v_lshlrev_b32_e32 v86, 16, v82
	v_and_b32_e32 v82, 0xffff0000, v82
	v_fma_f32 v212, v191, v86, v212
	v_fma_f32 v213, v191, v82, v213
	v_lshlrev_b32_e32 v87, 16, v83
	v_and_b32_e32 v83, 0xffff0000, v83
	v_fma_f32 v214, v191, v87, v214
	v_fma_f32 v215, v191, v83, v215
	global_store_dwordx4 v11, v[208:211], s[100:101] nt
	global_store_dwordx4 v11, v[212:215], s[100:101] offset:16 nt
	s_add_u32 s100, s100, 0x800000
	s_addc_u32 s101, s101, 0
	s_waitcnt vmcnt(37)
	v_lshlrev_b32_e32 v200, 16, v92
	v_and_b32_e32 v201, 0xffff0000, v92
	v_lshlrev_b32_e32 v202, 16, v93
	v_and_b32_e32 v203, 0xffff0000, v93
	v_lshlrev_b32_e32 v204, 16, v94
	v_and_b32_e32 v205, 0xffff0000, v94
	v_lshlrev_b32_e32 v206, 16, v95
	v_and_b32_e32 v207, 0xffff0000, v95
	v_lshlrev_b32_e32 v92, 16, v88
	v_and_b32_e32 v88, 0xffff0000, v88
	v_fma_f32 v200, v192, v92, v200
	v_fma_f32 v201, v192, v88, v201
	v_lshlrev_b32_e32 v93, 16, v89
	v_and_b32_e32 v89, 0xffff0000, v89
	v_fma_f32 v202, v192, v93, v202
	v_fma_f32 v203, v192, v89, v203
	v_lshlrev_b32_e32 v94, 16, v90
	v_and_b32_e32 v90, 0xffff0000, v90
	v_fma_f32 v204, v192, v94, v204
	v_fma_f32 v205, v192, v90, v205
	v_lshlrev_b32_e32 v95, 16, v91
	v_and_b32_e32 v91, 0xffff0000, v91
	v_fma_f32 v206, v192, v95, v206
	v_fma_f32 v207, v192, v91, v207
	global_store_dwordx4 v11, v[200:203], s[100:101] nt
	global_store_dwordx4 v11, v[204:207], s[100:101] offset:16 nt
	s_add_u32 s100, s100, 0x800000
	s_addc_u32 s101, s101, 0
	s_waitcnt vmcnt(36)
	v_lshlrev_b32_e32 v208, 16, v100
	v_and_b32_e32 v209, 0xffff0000, v100
	v_lshlrev_b32_e32 v210, 16, v101
	v_and_b32_e32 v211, 0xffff0000, v101
	v_lshlrev_b32_e32 v212, 16, v102
	v_and_b32_e32 v213, 0xffff0000, v102
	v_lshlrev_b32_e32 v214, 16, v103
	v_and_b32_e32 v215, 0xffff0000, v103
	v_lshlrev_b32_e32 v100, 16, v96
	v_and_b32_e32 v96, 0xffff0000, v96
	v_fma_f32 v208, v193, v100, v208
	v_fma_f32 v209, v193, v96, v209
	v_lshlrev_b32_e32 v101, 16, v97
	v_and_b32_e32 v97, 0xffff0000, v97
	v_fma_f32 v210, v193, v101, v210
	v_fma_f32 v211, v193, v97, v211
	v_lshlrev_b32_e32 v102, 16, v98
	v_and_b32_e32 v98, 0xffff0000, v98
	v_fma_f32 v212, v193, v102, v212
	v_fma_f32 v213, v193, v98, v213
	v_lshlrev_b32_e32 v103, 16, v99
	v_and_b32_e32 v99, 0xffff0000, v99
	v_fma_f32 v214, v193, v103, v214
	v_fma_f32 v215, v193, v99, v215
	global_store_dwordx4 v11, v[208:211], s[100:101] nt
	global_store_dwordx4 v11, v[212:215], s[100:101] offset:16 nt
	s_add_u32 s100, s100, 0x800000
	s_addc_u32 s101, s101, 0
	s_waitcnt vmcnt(35)
	v_lshlrev_b32_e32 v200, 16, v108
	v_and_b32_e32 v201, 0xffff0000, v108
	v_lshlrev_b32_e32 v202, 16, v109
	v_and_b32_e32 v203, 0xffff0000, v109
	v_lshlrev_b32_e32 v204, 16, v110
	v_and_b32_e32 v205, 0xffff0000, v110
	v_lshlrev_b32_e32 v206, 16, v111
	v_and_b32_e32 v207, 0xffff0000, v111
	v_lshlrev_b32_e32 v108, 16, v104
	v_and_b32_e32 v104, 0xffff0000, v104
	v_fma_f32 v200, v194, v108, v200
	v_fma_f32 v201, v194, v104, v201
	v_lshlrev_b32_e32 v109, 16, v105
	v_and_b32_e32 v105, 0xffff0000, v105
	v_fma_f32 v202, v194, v109, v202
	v_fma_f32 v203, v194, v105, v203
	v_lshlrev_b32_e32 v110, 16, v106
	v_and_b32_e32 v106, 0xffff0000, v106
	v_fma_f32 v204, v194, v110, v204
	v_fma_f32 v205, v194, v106, v205
	v_lshlrev_b32_e32 v111, 16, v107
	v_and_b32_e32 v107, 0xffff0000, v107
	v_fma_f32 v206, v194, v111, v206
	v_fma_f32 v207, v194, v107, v207
	global_store_dwordx4 v11, v[200:203], s[100:101] nt
	global_store_dwordx4 v11, v[204:207], s[100:101] offset:16 nt
	s_add_u32 s100, s100, 0x800000
	s_addc_u32 s101, s101, 0
	s_waitcnt vmcnt(34)
	v_lshlrev_b32_e32 v208, 16, v116
	v_and_b32_e32 v209, 0xffff0000, v116
	v_lshlrev_b32_e32 v210, 16, v117
	v_and_b32_e32 v211, 0xffff0000, v117
	v_lshlrev_b32_e32 v212, 16, v118
	v_and_b32_e32 v213, 0xffff0000, v118
	v_lshlrev_b32_e32 v214, 16, v119
	v_and_b32_e32 v215, 0xffff0000, v119
	v_lshlrev_b32_e32 v116, 16, v112
	v_and_b32_e32 v112, 0xffff0000, v112
	v_fma_f32 v208, v195, v116, v208
	v_fma_f32 v209, v195, v112, v209
	v_lshlrev_b32_e32 v117, 16, v113
	v_and_b32_e32 v113, 0xffff0000, v113
	v_fma_f32 v210, v195, v117, v210
	v_fma_f32 v211, v195, v113, v211
	v_lshlrev_b32_e32 v118, 16, v114
	v_and_b32_e32 v114, 0xffff0000, v114
	v_fma_f32 v212, v195, v118, v212
	v_fma_f32 v213, v195, v114, v213
	v_lshlrev_b32_e32 v119, 16, v115
	v_and_b32_e32 v115, 0xffff0000, v115
	v_fma_f32 v214, v195, v119, v214
	v_fma_f32 v215, v195, v115, v215
	global_store_dwordx4 v11, v[208:211], s[100:101] nt
	global_store_dwordx4 v11, v[212:215], s[100:101] offset:16 nt
	s_add_u32 s100, s100, 0x800000
	s_addc_u32 s101, s101, 0
	s_waitcnt vmcnt(33)
	v_lshlrev_b32_e32 v200, 16, v124
	v_and_b32_e32 v201, 0xffff0000, v124
	v_lshlrev_b32_e32 v202, 16, v125
	v_and_b32_e32 v203, 0xffff0000, v125
	v_lshlrev_b32_e32 v204, 16, v126
	v_and_b32_e32 v205, 0xffff0000, v126
	v_lshlrev_b32_e32 v206, 16, v127
	v_and_b32_e32 v207, 0xffff0000, v127
	v_lshlrev_b32_e32 v124, 16, v120
	v_and_b32_e32 v120, 0xffff0000, v120
	v_fma_f32 v200, v196, v124, v200
	v_fma_f32 v201, v196, v120, v201
	v_lshlrev_b32_e32 v125, 16, v121
	v_and_b32_e32 v121, 0xffff0000, v121
	v_fma_f32 v202, v196, v125, v202
	v_fma_f32 v203, v196, v121, v203
	v_lshlrev_b32_e32 v126, 16, v122
	v_and_b32_e32 v122, 0xffff0000, v122
	v_fma_f32 v204, v196, v126, v204
	v_fma_f32 v205, v196, v122, v205
	v_lshlrev_b32_e32 v127, 16, v123
	v_and_b32_e32 v123, 0xffff0000, v123
	v_fma_f32 v206, v196, v127, v206
	v_fma_f32 v207, v196, v123, v207
	global_store_dwordx4 v11, v[200:203], s[100:101] nt
	global_store_dwordx4 v11, v[204:207], s[100:101] offset:16 nt
	s_add_u32 s100, s100, 0x800000
	s_addc_u32 s101, s101, 0
	s_waitcnt vmcnt(32)
	v_lshlrev_b32_e32 v208, 16, v136
	v_and_b32_e32 v209, 0xffff0000, v136
	v_lshlrev_b32_e32 v210, 16, v137
	v_and_b32_e32 v211, 0xffff0000, v137
	v_lshlrev_b32_e32 v212, 16, v138
	v_and_b32_e32 v213, 0xffff0000, v138
	v_lshlrev_b32_e32 v214, 16, v139
	v_and_b32_e32 v215, 0xffff0000, v139
	v_lshlrev_b32_e32 v136, 16, v132
	v_and_b32_e32 v132, 0xffff0000, v132
	v_fma_f32 v208, v197, v136, v208
	v_fma_f32 v209, v197, v132, v209
	v_lshlrev_b32_e32 v137, 16, v133
	v_and_b32_e32 v133, 0xffff0000, v133
	v_fma_f32 v210, v197, v137, v210
	v_fma_f32 v211, v197, v133, v211
	v_lshlrev_b32_e32 v138, 16, v134
	v_and_b32_e32 v134, 0xffff0000, v134
	v_fma_f32 v212, v197, v138, v212
	v_fma_f32 v213, v197, v134, v213
	v_lshlrev_b32_e32 v139, 16, v135
	v_and_b32_e32 v135, 0xffff0000, v135
	v_fma_f32 v214, v197, v139, v214
	v_fma_f32 v215, v197, v135, v215
	global_store_dwordx4 v11, v[208:211], s[100:101] nt
	global_store_dwordx4 v11, v[212:215], s[100:101] offset:16 nt
	s_add_u32 s100, s100, 0x800000
	s_addc_u32 s101, s101, 0
	s_waitcnt vmcnt(31)
	v_lshlrev_b32_e32 v200, 16, v144
	v_and_b32_e32 v201, 0xffff0000, v144
	v_lshlrev_b32_e32 v202, 16, v145
	v_and_b32_e32 v203, 0xffff0000, v145
	v_lshlrev_b32_e32 v204, 16, v146
	v_and_b32_e32 v205, 0xffff0000, v146
	v_lshlrev_b32_e32 v206, 16, v147
	v_and_b32_e32 v207, 0xffff0000, v147
	v_lshlrev_b32_e32 v144, 16, v140
	v_and_b32_e32 v140, 0xffff0000, v140
	v_fma_f32 v200, v198, v144, v200
	v_fma_f32 v201, v198, v140, v201
	v_lshlrev_b32_e32 v145, 16, v141
	v_and_b32_e32 v141, 0xffff0000, v141
	v_fma_f32 v202, v198, v145, v202
	v_fma_f32 v203, v198, v141, v203
	v_lshlrev_b32_e32 v146, 16, v142
	v_and_b32_e32 v142, 0xffff0000, v142
	v_fma_f32 v204, v198, v146, v204
	v_fma_f32 v205, v198, v142, v205
	v_lshlrev_b32_e32 v147, 16, v143
	v_and_b32_e32 v143, 0xffff0000, v143
	v_fma_f32 v206, v198, v147, v206
	v_fma_f32 v207, v198, v143, v207
	global_store_dwordx4 v11, v[200:203], s[100:101] nt
	global_store_dwordx4 v11, v[204:207], s[100:101] offset:16 nt
	s_add_u32 s100, s100, 0x800000
	s_addc_u32 s101, s101, 0
	s_waitcnt vmcnt(30)
	v_lshlrev_b32_e32 v208, 16, v152
	v_and_b32_e32 v209, 0xffff0000, v152
	v_lshlrev_b32_e32 v210, 16, v153
	v_and_b32_e32 v211, 0xffff0000, v153
	v_lshlrev_b32_e32 v212, 16, v154
	v_and_b32_e32 v213, 0xffff0000, v154
	v_lshlrev_b32_e32 v214, 16, v155
	v_and_b32_e32 v215, 0xffff0000, v155
	v_lshlrev_b32_e32 v152, 16, v148
	v_and_b32_e32 v148, 0xffff0000, v148
	v_fma_f32 v208, v199, v152, v208
	v_fma_f32 v209, v199, v148, v209
	v_lshlrev_b32_e32 v153, 16, v149
	v_and_b32_e32 v149, 0xffff0000, v149
	v_fma_f32 v210, v199, v153, v210
	v_fma_f32 v211, v199, v149, v211
	v_lshlrev_b32_e32 v154, 16, v150
	v_and_b32_e32 v150, 0xffff0000, v150
	v_fma_f32 v212, v199, v154, v212
	v_fma_f32 v213, v199, v150, v213
	v_lshlrev_b32_e32 v155, 16, v151
	v_and_b32_e32 v151, 0xffff0000, v151
	v_fma_f32 v214, v199, v155, v214
	v_fma_f32 v215, v199, v151, v215
	global_store_dwordx4 v11, v[208:211], s[100:101] nt
	global_store_dwordx4 v11, v[212:215], s[100:101] offset:16 nt
	v_add_u32_e32 v67, 0x200000, v67
	v_add_u32_e32 v71, 0x1000000, v71
	s_branch .LBB0_2042

.LBB0_2101:
	s_ashr_i32 s12, s13, 3
	s_lshl_b32 s14, s12, 7
	v_add_u32_e32 v0, s14, v170
	v_ashrrev_i32_e32 v1, 31, v0
	v_readlane_b32 s16, v252, 47
	v_writelane_b32 v255, s13, 49
	s_and_b32 s13, s13, 7
	v_lshlrev_b64 v[0:1], 11, v[0:1]
	v_readlane_b32 s17, v252, 48
	v_readlane_b32 s22, v252, 12
	v_readlane_b32 s23, v252, 13
	v_lshl_add_u64 v[0:1], s[16:17], 0, v[0:1]
	s_lshl_b32 s22, s13, 8
	v_lshl_add_u64 v[0:1], v[0:1], 0, s[22:23]
	v_lshlrev_b32_e32 v2, 1, v172
	v_mov_b32_e32 v3, v129
	v_lshl_add_u64 v[0:1], v[0:1], 0, v[2:3]
	global_load_dwordx4 v[130:133], v[0:1], off
	global_load_dwordx4 v[134:137], v[0:1], off offset:32
	global_load_dwordx4 v[138:141], v[0:1], off offset:64
	global_load_dwordx4 v[142:145], v[0:1], off offset:96
	global_load_dwordx4 v[146:149], v[0:1], off offset:128
	global_load_dwordx4 v[150:153], v[0:1], off offset:160
	global_load_dwordx4 v[154:157], v[0:1], off offset:192
	global_load_dwordx4 v[158:161], v[0:1], off offset:224
	v_or_b32_e32 v0, s14, v173
	v_ashrrev_i32_e32 v1, 31, v0
	v_readlane_b32 s16, v252, 45
	v_lshlrev_b64 v[0:1], 11, v[0:1]
	v_readlane_b32 s17, v252, 46
	s_mov_b32 s15, 0x10000
	s_lshl_b32 s13, s13, 2
	v_lshl_add_u64 v[0:1], s[16:17], 0, v[0:1]
	v_lshl_add_u64 v[0:1], v[0:1], 0, s[22:23]
	v_lshl_add_u64 v[64:65], v[0:1], 0, v[2:3]
	v_add_co_u32_e32 v66, vcc, s15, v64
	s_mov_b32 s15, 0x20000
	s_nop 0
	v_addc_co_u32_e32 v67, vcc, 0, v65, vcc
	v_add_co_u32_e32 v68, vcc, s15, v64
	s_mov_b32 s15, 0x30000
	s_nop 0
	v_addc_co_u32_e32 v69, vcc, 0, v65, vcc
	v_add_co_u32_e32 v70, vcc, s15, v64
	v_writelane_b32 v255, s13, 50
	s_nop 0
	v_addc_co_u32_e32 v71, vcc, 0, v65, vcc
	s_ashr_i32 s13, s12, 31
	s_lshl_b64 s[20:21], s[12:13], 19
	v_readlane_b32 s16, v252, 43
	s_add_u32 s15, s16, s20
	v_writelane_b32 v255, s15, 51
	v_readlane_b32 s17, v252, 44
	v_writelane_b32 v255, s20, 52
	s_addc_u32 s15, s17, s21
	s_lshl_b64 s[16:17], s[12:13], 20
	v_writelane_b32 v255, s21, 53
	v_readlane_b32 s20, v252, 49
	v_writelane_b32 v255, s15, 54
	v_readlane_b32 s21, v252, 50
	s_add_u32 s15, s20, s16
	v_writelane_b32 v255, s15, 55
	s_addc_u32 s15, s21, s17
	v_writelane_b32 v255, s15, 56
	s_cmp_lt_u32 s12, 64
	s_cselect_b32 s15, 1, 0
	s_and_b32 s16, s12, 1
	s_xor_b32 s17, s16, 1
	s_and_b32 s17, s17, s15
	s_and_b32 s16, s16, s15
	s_add_i32 s20, s17, -1
	v_writelane_b32 v255, s20, 58
	s_add_i32 s20, s16, -1
	v_writelane_b32 v255, s20, 59
	s_mov_b32 s20, 1
	s_lshl_b32 s20, s20, 19
	v_writelane_b32 v255, s20, 60
	s_mov_b32 s17, 0
	s_xor_b32 s20, s12, s15
	s_mov_b32 s21, 0
	s_lshl_b64 s[20:21], s[20:21], 19
	v_writelane_b32 v255, s20, 52
	v_writelane_b32 v255, s21, 53
	s_lshl_b64 s[20:21], s[20:21], 1
	s_add_u32 s20, s20, s17
	s_addc_u32 s21, s21, 0
	v_readlane_b32 s16, v252, 49
	v_readlane_b32 s17, v252, 50
	s_add_u32 s20, s20, s16
	s_addc_u32 s21, s21, s17
	v_writelane_b32 v255, s20, 55
	v_writelane_b32 v255, s21, 56
	s_mov_b32 s19, 0
	s_lshl_b64 s[12:13], s[12:13], 13
	global_load_dwordx4 v[76:79], v[64:65], off
	global_load_dwordx4 v[80:83], v[66:67], off
	global_load_dwordx4 v[84:87], v[68:69], off
	global_load_dwordx4 v[88:91], v[70:71], off
	global_load_dwordx4 v[92:95], v[64:65], off offset:32
	global_load_dwordx4 v[96:99], v[66:67], off offset:32
	global_load_dwordx4 v[100:103], v[68:69], off offset:32
	global_load_dwordx4 v[104:107], v[70:71], off offset:32
	global_load_dwordx4 v[108:111], v[64:65], off offset:64
	global_load_dwordx4 v[112:115], v[66:67], off offset:64
	global_load_dwordx4 v[116:119], v[68:69], off offset:64
	global_load_dwordx4 v[120:123], v[70:71], off offset:64
	global_load_dwordx4 v[124:127], v[64:65], off offset:96
	global_load_dwordx4 v[72:75], v[66:67], off offset:96
	global_load_dwordx4 v[212:215], v[68:69], off offset:96
	global_load_dwordx4 v[222:225], v[70:71], off offset:96
	global_load_dwordx4 v[234:237], v[64:65], off offset:128
	global_load_dwordx4 v[238:241], v[66:67], off offset:128
	global_load_dwordx4 v[242:245], v[68:69], off offset:128
	global_load_dwordx4 v[246:249], v[70:71], off offset:128
	s_waitcnt vmcnt(19)
	v_mfma_f32_32x32x16_bf16 v[0:15], v[76:79], v[130:133], 0
	global_load_dwordx4 v[76:79], v[64:65], off offset:160
	s_waitcnt vmcnt(19)
	v_mfma_f32_32x32x16_bf16 v[16:31], v[80:83], v[130:133], 0
	global_load_dwordx4 v[80:83], v[66:67], off offset:160
	s_waitcnt vmcnt(19)
	v_mfma_f32_32x32x16_bf16 v[32:47], v[84:87], v[130:133], 0
	global_load_dwordx4 v[84:87], v[68:69], off offset:160
	s_waitcnt vmcnt(19)
	v_mfma_f32_32x32x16_bf16 v[48:63], v[88:91], v[130:133], 0
	global_load_dwordx4 v[88:91], v[70:71], off offset:160
	s_waitcnt vmcnt(19)
	v_mfma_f32_32x32x16_bf16 v[0:15], v[92:95], v[134:137], v[0:15]
	global_load_dwordx4 v[92:95], v[64:65], off offset:192
	s_waitcnt vmcnt(19)
	v_mfma_f32_32x32x16_bf16 v[16:31], v[96:99], v[134:137], v[16:31]
	global_load_dwordx4 v[96:99], v[66:67], off offset:192
	s_waitcnt vmcnt(19)
	v_mfma_f32_32x32x16_bf16 v[32:47], v[100:103], v[134:137], v[32:47]
	global_load_dwordx4 v[100:103], v[68:69], off offset:192
	s_waitcnt vmcnt(19)
	v_mfma_f32_32x32x16_bf16 v[48:63], v[104:107], v[134:137], v[48:63]
	global_load_dwordx4 v[104:107], v[70:71], off offset:192
	s_waitcnt vmcnt(19)
	v_mfma_f32_32x32x16_bf16 v[0:15], v[108:111], v[138:141], v[0:15]
	global_load_dwordx4 v[108:111], v[64:65], off offset:224
	s_waitcnt vmcnt(19)
	v_mfma_f32_32x32x16_bf16 v[16:31], v[112:115], v[138:141], v[16:31]
	global_load_dwordx4 v[112:115], v[66:67], off offset:224
	s_waitcnt vmcnt(19)
	v_mfma_f32_32x32x16_bf16 v[32:47], v[116:119], v[138:141], v[32:47]
	global_load_dwordx4 v[116:119], v[68:69], off offset:224
	s_waitcnt vmcnt(19)
	v_mfma_f32_32x32x16_bf16 v[48:63], v[120:123], v[138:141], v[48:63]
	global_load_dwordx4 v[120:123], v[70:71], off offset:224
	s_waitcnt vmcnt(19)
	v_mfma_f32_32x32x16_bf16 v[0:15], v[124:127], v[142:145], v[0:15]
	s_waitcnt vmcnt(18)
	v_mfma_f32_32x32x16_bf16 v[16:31], v[72:75], v[142:145], v[16:31]
	s_waitcnt vmcnt(17)
	v_mfma_f32_32x32x16_bf16 v[32:47], v[212:215], v[142:145], v[32:47]
	s_waitcnt vmcnt(16)
	v_mfma_f32_32x32x16_bf16 v[48:63], v[222:225], v[142:145], v[48:63]
	s_waitcnt vmcnt(15)
	v_mfma_f32_32x32x16_bf16 v[0:15], v[234:237], v[146:149], v[0:15]
	s_waitcnt vmcnt(14)
	v_mfma_f32_32x32x16_bf16 v[16:31], v[238:241], v[146:149], v[16:31]
	s_waitcnt vmcnt(13)
	v_mfma_f32_32x32x16_bf16 v[32:47], v[242:245], v[146:149], v[32:47]
	s_waitcnt vmcnt(12)
	v_mfma_f32_32x32x16_bf16 v[48:63], v[246:249], v[146:149], v[48:63]
	s_waitcnt vmcnt(11)
	v_mfma_f32_32x32x16_bf16 v[0:15], v[76:79], v[150:153], v[0:15]
	s_waitcnt vmcnt(10)
	v_mfma_f32_32x32x16_bf16 v[16:31], v[80:83], v[150:153], v[16:31]
	s_waitcnt vmcnt(9)
	v_mfma_f32_32x32x16_bf16 v[32:47], v[84:87], v[150:153], v[32:47]
	s_waitcnt vmcnt(8)
	v_mfma_f32_32x32x16_bf16 v[48:63], v[88:91], v[150:153], v[48:63]
	s_waitcnt vmcnt(7)
	v_mfma_f32_32x32x16_bf16 v[0:15], v[92:95], v[154:157], v[0:15]
	s_waitcnt vmcnt(6)
	v_mfma_f32_32x32x16_bf16 v[16:31], v[96:99], v[154:157], v[16:31]
	s_waitcnt vmcnt(5)
	v_mfma_f32_32x32x16_bf16 v[32:47], v[100:103], v[154:157], v[32:47]
	s_waitcnt vmcnt(4)
	v_mfma_f32_32x32x16_bf16 v[48:63], v[104:107], v[154:157], v[48:63]
	s_waitcnt vmcnt(3)
	v_mfma_f32_32x32x16_bf16 v[0:15], v[108:111], v[158:161], v[0:15]
	s_waitcnt vmcnt(2)
	v_mfma_f32_32x32x16_bf16 v[16:31], v[112:115], v[158:161], v[16:31]
	s_waitcnt vmcnt(1)
	v_mfma_f32_32x32x16_bf16 v[32:47], v[116:119], v[158:161], v[32:47]
	s_waitcnt vmcnt(0)
	v_mfma_f32_32x32x16_bf16 v[48:63], v[120:123], v[158:161], v[48:63]
	v_add_u32_e32 v64, s14, v200
	v_ashrrev_i32_e32 v65, 31, v64
	v_readlane_b32 s14, v252, 41
	v_lshlrev_b64 v[64:65], 12, v[64:65]
	v_readlane_b32 s15, v252, 42
	s_nop 1
	v_lshl_add_u64 v[184:185], s[14:15], 0, v[64:65]
	s_branch .LBB0_2103
